# LRU: replace 16 IEEE-refined sqrt sequences by raw v_sqrt_f32 (f32, 1ulp)
# speedup vs baseline: 1.0046x; 1.0046x over previous
; __device__ __forceinline__ float bf2f(bf16_t b) { return __uint_as_float(((unsigned)b) << 16); }
; __device__ __forceinline__ float sigmoidf(float z) { return __builtin_amdgcn_rcpf(1.0f + __expf(-z)); }
; __device__ void lru_fused_phase(const int bid, const int nblk, bf16_t* __restrict__ U, bf16_t* __restrict__ HF, const bf16_t* __restrict__ Wg, const float* __restrict__ cw, const float* __restrict__ cb, ...
;     ...
; #pragma unroll
;                     for (int s = 0; s < 4; ++s) {
;                         const bf16x8 af = *(const bf16x8*)(buf + (16 * rt + fr) * RS + (32 * s + 8 * fq) * 2);
;                         za = __builtin_amdgcn_mfma_f32_16x16x32_bf16(af, Bf[0][s], za, 0, 0, 0);
;                         zi = __builtin_amdgcn_mfma_f32_16x16x32_bf16(af, Bf[1][s], zi, 0, 0, 0);
;                     }
;                     float av[4], bv[4];
; #pragma unroll
;                     for (int j = 0; j < 4; ++j) {
;                         const float c = bf2f(*(const unsigned short*)(buf + (16 * rt + 4 * fq + j) * RS + chl * 2));
;                         const float r = sigmoidf(za[j] + ba), ig = sigmoidf(zi[j] + bi_);
;                         const float la = -sp * r;
;                         av[j] = __expf(la);
;                         bv[j] = __builtin_sqrtf(fmaxf(1.0f - av[j] * av[j], 0.f)) * ig * c;
;                     }
.LBB0_119:
	s_bitcmp1_b32 s2, 0
	s_cselect_b32 s2, 0x4400, 0
	s_add_i32 s2, s2, 0
	v_add_u32_e32 v104, s2, v8
	v_add_u32_e32 v106, v104, v98
	ds_read_b128 v[36:39], v106
	ds_read_b128 v[108:111], v106 offset:64
	v_add_u32_e32 v10, s2, v74
	s_mov_b64 s[2:3], -1
	s_waitcnt lgkmcnt(1)
	v_mfma_f32_16x16x32_bf16 v[40:43], v[36:39], v[0:3], 0
	v_mfma_f32_16x16x32_bf16 v[36:39], v[36:39], v[20:23], 0
	s_waitcnt lgkmcnt(0)
	v_mfma_f32_16x16x32_bf16 v[40:43], v[108:111], v[4:7], v[40:43]
	v_mfma_f32_16x16x32_bf16 v[36:39], v[108:111], v[24:27], v[36:39]
	ds_read_b128 v[108:111], v106 offset:128
	s_waitcnt lgkmcnt(0)
	v_mfma_f32_16x16x32_bf16 v[40:43], v[108:111], v[12:15], v[40:43]
	v_mfma_f32_16x16x32_bf16 v[36:39], v[108:111], v[28:31], v[36:39]
	ds_read_b128 v[108:111], v106 offset:192
	v_add_u32_e32 v106, v10, v99
	s_waitcnt lgkmcnt(0)
	v_mfma_f32_16x16x32_bf16 v[40:43], v[108:111], v[16:19], v[40:43]
	s_nop 7
	v_add_f32_e32 v40, v82, v40
	v_mfma_f32_16x16x32_bf16 v[36:39], v[108:111], v[32:35], v[36:39]
	v_mul_f32_e32 v40, 0xbfb8aa3b, v40
	v_exp_f32_e32 v40, v40
	v_add_f32_e32 v41, v82, v41
	v_mul_f32_e32 v41, 0xbfb8aa3b, v41
	v_exp_f32_e32 v41, v41
	s_nop 2
	v_add_f32_e32 v36, v83, v36
	v_mul_f32_e32 v36, 0xbfb8aa3b, v36
	v_add_f32_e32 v40, 1.0, v40
	v_exp_f32_e32 v36, v36
	v_rcp_f32_e32 v40, v40
	v_add_f32_e32 v37, v83, v37
	v_mul_f32_e32 v37, 0xbfb8aa3b, v37
	v_add_f32_e32 v36, 1.0, v36
	v_rcp_f32_e32 v109, v36
	v_mul_f32_e32 v36, v40, v86
	v_mul_f32_e32 v36, 0xbfb8aa3b, v36
	v_exp_f32_e32 v36, v36
	v_add_f32_e32 v41, 1.0, v41
	v_exp_f32_e32 v37, v37
	v_rcp_f32_e32 v41, v41
	v_fma_f32 v40, -v36, v36, 1.0
	v_max_f32_e32 v40, 0, v40
	v_add_f32_e32 v37, 1.0, v37
	v_sqrt_f32_e32 v40, v40
	s_nop 0
	v_add_f32_e32 v42, v82, v42
	v_mul_f32_e32 v42, 0xbfb8aa3b, v42
	v_exp_f32_e32 v42, v42
	v_add_f32_e32 v38, v83, v38
	v_mul_f32_e32 v38, 0xbfb8aa3b, v38
	v_add_f32_e32 v42, 1.0, v42
	v_exp_f32_e32 v38, v38
	v_rcp_f32_e32 v42, v42
	v_mul_f32_e32 v40, v109, v40
	v_rcp_f32_e32 v109, v37
	v_mul_f32_e32 v37, v41, v86
	v_mul_f32_e32 v37, 0xbfb8aa3b, v37
	v_exp_f32_e32 v37, v37
	v_add_f32_e32 v38, 1.0, v38
	ds_read_u16 v108, v106
	v_add_f32_e32 v43, v82, v43
	v_fma_f32 v41, -v37, v37, 1.0
	v_max_f32_e32 v41, 0, v41
	s_waitcnt lgkmcnt(0)
	v_lshlrev_b32_e32 v108, 16, v108
	v_sqrt_f32_e32 v41, v41
	s_nop 0
	v_mul_f32_e32 v40, v40, v108
	ds_read_u16 v108, v106 offset:272
	v_mul_f32_e32 v43, 0xbfb8aa3b, v43
	v_exp_f32_e32 v43, v43
	s_waitcnt lgkmcnt(0)
	v_lshlrev_b32_e32 v108, 16, v108
	v_add_f32_e32 v39, v83, v39
	v_mul_f32_e32 v39, 0xbfb8aa3b, v39
	v_add_f32_e32 v43, 1.0, v43
	v_mul_f32_e32 v41, v109, v41
	v_rcp_f32_e32 v109, v38
	v_mul_f32_e32 v38, v42, v86
	v_mul_f32_e32 v38, 0xbfb8aa3b, v38
	v_exp_f32_e32 v38, v38
	v_mul_f32_e32 v41, v41, v108
	ds_read_u16 v108, v106 offset:544
	v_exp_f32_e32 v39, v39
	v_fma_f32 v42, -v38, v38, 1.0
	v_max_f32_e32 v42, 0, v42
	v_rcp_f32_e32 v43, v43
	v_sqrt_f32_e32 v42, v42
	s_nop 0
	s_waitcnt lgkmcnt(0)
	v_lshlrev_b32_e32 v108, 16, v108
	v_add_f32_e32 v39, 1.0, v39
	ds_read_u16 v106, v106 offset:816
	s_waitcnt lgkmcnt(0)
	v_lshlrev_b32_e32 v106, 16, v106
	s_nop 1
	s_nop 1
	v_mul_f32_e32 v42, v109, v42
	v_mul_f32_e32 v42, v42, v108
	v_rcp_f32_e32 v108, v39
	v_mul_f32_e32 v39, v43, v86
	v_mul_f32_e32 v39, 0xbfb8aa3b, v39
	v_exp_f32_e32 v39, v39
	s_nop 0
	v_fma_f32 v43, -v39, v39, 1.0
	v_max_f32_e32 v43, 0, v43
	s_nop 0
	v_sqrt_f32_e32 v43, v43
	s_nop 0
	s_nop 0
	s_nop 0
	s_nop 1
	s_nop 1
	v_mul_f32_e32 v43, v108, v43
	v_mul_f32_e32 v43, v43, v106
	s_and_b64 vcc, exec, s[64:65]
	s_cbranch_vccz .LBB0_121
	v_fma_f32 v108, v38, v43, v42
	v_mul_f32_e32 v109, v38, v39
	v_fma_f32 v111, v37, v108, v41
	v_mul_f32_e32 v110, v37, v109
	v_fma_f32 v112, v36, v111, v40
	v_mul_f32_e32 v106, v36, v110
	s_mov_b64 s[2:3], 0

; __device__ __forceinline__ float bf2f(bf16_t b) { return __uint_as_float(((unsigned)b) << 16); }
; __device__ __forceinline__ float sigmoidf(float z) { return __builtin_amdgcn_rcpf(1.0f + __expf(-z)); }
; __device__ void lru_fused_phase(const int bid, const int nblk, bf16_t* __restrict__ U, bf16_t* __restrict__ HF, const bf16_t* __restrict__ Wg, const float* __restrict__ cw, const float* __restrict__ cb, ...
;     ...
; #pragma unroll
;                     for (int s = 0; s < 4; ++s) {
;                         const bf16x8 af = *(const bf16x8*)(buf + (16 * rt + fr) * RS + (32 * s + 8 * fq) * 2);
;                         za = __builtin_amdgcn_mfma_f32_16x16x32_bf16(af, Bf[0][s], za, 0, 0, 0);
;                         zi = __builtin_amdgcn_mfma_f32_16x16x32_bf16(af, Bf[1][s], zi, 0, 0, 0);
;                     }
;                     float av[4], bv[4];
; #pragma unroll
;                     for (int j = 0; j < 4; ++j) {
;                         const float c = bf2f(*(const unsigned short*)(buf + (16 * rt + 4 * fq + j) * RS + chl * 2));
;                         const float r = sigmoidf(za[j] + ba), ig = sigmoidf(zi[j] + bi_);
;                         const float la = -sp * r;
;                         av[j] = __expf(la);
;                         bv[j] = __builtin_sqrtf(fmaxf(1.0f - av[j] * av[j], 0.f)) * ig * c;
;                     }
.LBB0_142:
	v_or_b32_e32 v36, s38, v47
	v_mad_u32_u24 v105, v36, s35, v104
	ds_read_b128 v[36:39], v105
	ds_read_b128 v[108:111], v105 offset:64
	s_mov_b64 s[2:3], -1
	s_waitcnt lgkmcnt(1)
	v_mfma_f32_16x16x32_bf16 v[40:43], v[36:39], v[0:3], 0
	v_mfma_f32_16x16x32_bf16 v[36:39], v[36:39], v[20:23], 0
	s_waitcnt lgkmcnt(0)
	v_mfma_f32_16x16x32_bf16 v[40:43], v[108:111], v[4:7], v[40:43]
	v_mfma_f32_16x16x32_bf16 v[36:39], v[108:111], v[24:27], v[36:39]
	ds_read_b128 v[108:111], v105 offset:128
	s_waitcnt lgkmcnt(0)
	v_mfma_f32_16x16x32_bf16 v[40:43], v[108:111], v[12:15], v[40:43]
	v_mfma_f32_16x16x32_bf16 v[36:39], v[108:111], v[28:31], v[36:39]
	ds_read_b128 v[108:111], v105 offset:192
	v_or_b32_e32 v105, s38, v46
	v_mad_u32_u24 v105, v105, s35, v10
	s_waitcnt lgkmcnt(0)
	v_mfma_f32_16x16x32_bf16 v[40:43], v[108:111], v[16:19], v[40:43]
	s_nop 7
	v_add_f32_e32 v40, v82, v40
	v_mfma_f32_16x16x32_bf16 v[36:39], v[108:111], v[32:35], v[36:39]
	v_mul_f32_e32 v40, 0xbfb8aa3b, v40
	v_exp_f32_e32 v40, v40
	v_add_f32_e32 v41, v82, v41
	v_mul_f32_e32 v41, 0xbfb8aa3b, v41
	v_exp_f32_e32 v41, v41
	s_nop 2
	v_add_f32_e32 v36, v83, v36
	v_mul_f32_e32 v36, 0xbfb8aa3b, v36
	v_add_f32_e32 v40, 1.0, v40
	v_exp_f32_e32 v36, v36
	v_rcp_f32_e32 v40, v40
	v_add_f32_e32 v37, v83, v37
	v_mul_f32_e32 v37, 0xbfb8aa3b, v37
	v_add_f32_e32 v36, 1.0, v36
	v_rcp_f32_e32 v109, v36
	v_mul_f32_e32 v36, v40, v86
	v_mul_f32_e32 v36, 0xbfb8aa3b, v36
	v_exp_f32_e32 v36, v36
	v_add_f32_e32 v41, 1.0, v41
	v_exp_f32_e32 v37, v37
	v_rcp_f32_e32 v41, v41
	v_fma_f32 v40, -v36, v36, 1.0
	v_max_f32_e32 v40, 0, v40
	v_add_f32_e32 v37, 1.0, v37
	v_sqrt_f32_e32 v40, v40
	s_nop 0
	v_add_f32_e32 v42, v82, v42
	v_mul_f32_e32 v42, 0xbfb8aa3b, v42
	v_exp_f32_e32 v42, v42
	v_add_f32_e32 v38, v83, v38
	v_mul_f32_e32 v38, 0xbfb8aa3b, v38
	v_add_f32_e32 v42, 1.0, v42
	v_exp_f32_e32 v38, v38
	v_rcp_f32_e32 v42, v42
	v_mul_f32_e32 v40, v109, v40
	v_rcp_f32_e32 v109, v37
	v_mul_f32_e32 v37, v41, v86
	v_mul_f32_e32 v37, 0xbfb8aa3b, v37
	v_exp_f32_e32 v37, v37
	v_add_f32_e32 v38, 1.0, v38
	ds_read_u16 v108, v105
	v_add_f32_e32 v43, v82, v43
	v_fma_f32 v41, -v37, v37, 1.0
	v_max_f32_e32 v41, 0, v41
	s_waitcnt lgkmcnt(0)
	v_lshlrev_b32_e32 v108, 16, v108
	v_sqrt_f32_e32 v41, v41
	s_nop 0
	v_mul_f32_e32 v40, v40, v108
	ds_read_u16 v108, v105 offset:272
	v_mul_f32_e32 v43, 0xbfb8aa3b, v43
	v_exp_f32_e32 v43, v43
	s_waitcnt lgkmcnt(0)
	v_lshlrev_b32_e32 v108, 16, v108
	v_add_f32_e32 v39, v83, v39
	v_mul_f32_e32 v39, 0xbfb8aa3b, v39
	v_add_f32_e32 v43, 1.0, v43
	v_mul_f32_e32 v41, v109, v41
	v_rcp_f32_e32 v109, v38
	v_mul_f32_e32 v38, v42, v86
	v_mul_f32_e32 v38, 0xbfb8aa3b, v38
	v_exp_f32_e32 v38, v38
	v_mul_f32_e32 v41, v41, v108
	ds_read_u16 v108, v105 offset:544
	v_exp_f32_e32 v39, v39
	v_fma_f32 v42, -v38, v38, 1.0
	v_max_f32_e32 v42, 0, v42
	v_rcp_f32_e32 v43, v43
	v_sqrt_f32_e32 v42, v42
	s_nop 0
	s_waitcnt lgkmcnt(0)
	v_lshlrev_b32_e32 v108, 16, v108
	v_add_f32_e32 v39, 1.0, v39
	ds_read_u16 v105, v105 offset:816
	s_waitcnt lgkmcnt(0)
	v_lshlrev_b32_e32 v105, 16, v105
	s_nop 1
	s_nop 1
	v_mul_f32_e32 v42, v109, v42
	v_mul_f32_e32 v42, v42, v108
	v_rcp_f32_e32 v108, v39
	v_mul_f32_e32 v39, v43, v86
	v_mul_f32_e32 v39, 0xbfb8aa3b, v39
	v_exp_f32_e32 v39, v39
	s_nop 0
	v_fma_f32 v43, -v39, v39, 1.0
	v_max_f32_e32 v43, 0, v43
	s_nop 0
	v_sqrt_f32_e32 v43, v43
	s_nop 0
	s_nop 0
	s_nop 0
	s_nop 1
	s_nop 1
	v_mul_f32_e32 v43, v108, v43
	v_mul_f32_e32 v43, v43, v105
	s_and_b64 vcc, exec, s[8:9]
	s_cbranch_vccnz .LBB0_144
	v_fma_f32 v108, v38, v43, v42
	v_mul_f32_e32 v109, v38, v39
	v_fma_f32 v111, v37, v108, v41
	v_mul_f32_e32 v110, v37, v109
	v_fma_f32 v112, v36, v111, v40
	v_mul_f32_e32 v105, v36, v110
	s_mov_b64 s[2:3], 0

; __device__ __forceinline__ float bf2f(bf16_t b) { return __uint_as_float(((unsigned)b) << 16); }
; __device__ __forceinline__ float sigmoidf(float z) { return __builtin_amdgcn_rcpf(1.0f + __expf(-z)); }
; __device__ void lru_fused_phase(const int bid, const int nblk, bf16_t* __restrict__ U, bf16_t* __restrict__ HF, const bf16_t* __restrict__ Wg, const float* __restrict__ cw, const float* __restrict__ cb, ...
;     ...
; #pragma unroll
;                     for (int s = 0; s < 4; ++s) {
;                         const bf16x8 af = *(const bf16x8*)(buf + (16 * rt + fr) * RS + (32 * s + 8 * fq) * 2);
;                         za = __builtin_amdgcn_mfma_f32_16x16x32_bf16(af, Bf[0][s], za, 0, 0, 0);
;                         zi = __builtin_amdgcn_mfma_f32_16x16x32_bf16(af, Bf[1][s], zi, 0, 0, 0);
;                     }
;                     float av[4], bv[4];
; #pragma unroll
;                     for (int j = 0; j < 4; ++j) {
;                         const float c = bf2f(*(const unsigned short*)(buf + (16 * rt + 4 * fq + j) * RS + chl * 2));
;                         const float r = sigmoidf(za[j] + ba), ig = sigmoidf(zi[j] + bi_);
;                         const float la = -sp * r;
;                         av[j] = __expf(la);
;                         bv[j] = __builtin_sqrtf(fmaxf(1.0f - av[j] * av[j], 0.f)) * ig * c;
;                     }
.LBB0_165:
	v_or_b32_e32 v36, s38, v47
	v_mad_u32_u24 v106, v36, s35, v104
	ds_read_b128 v[36:39], v106
	ds_read_b128 v[108:111], v106 offset:64
	s_mov_b64 s[2:3], -1
	s_waitcnt lgkmcnt(1)
	v_mfma_f32_16x16x32_bf16 v[40:43], v[36:39], v[0:3], 0
	v_mfma_f32_16x16x32_bf16 v[36:39], v[36:39], v[20:23], 0
	s_waitcnt lgkmcnt(0)
	v_mfma_f32_16x16x32_bf16 v[40:43], v[108:111], v[4:7], v[40:43]
	v_mfma_f32_16x16x32_bf16 v[36:39], v[108:111], v[24:27], v[36:39]
	ds_read_b128 v[108:111], v106 offset:128
	s_waitcnt lgkmcnt(0)
	v_mfma_f32_16x16x32_bf16 v[40:43], v[108:111], v[12:15], v[40:43]
	v_mfma_f32_16x16x32_bf16 v[36:39], v[108:111], v[28:31], v[36:39]
	ds_read_b128 v[108:111], v106 offset:192
	v_or_b32_e32 v106, s38, v46
	v_mad_u32_u24 v106, v106, s35, v10
	s_waitcnt lgkmcnt(0)
	v_mfma_f32_16x16x32_bf16 v[40:43], v[108:111], v[16:19], v[40:43]
	s_nop 7
	v_add_f32_e32 v40, v82, v40
	v_mfma_f32_16x16x32_bf16 v[36:39], v[108:111], v[32:35], v[36:39]
	v_mul_f32_e32 v40, 0xbfb8aa3b, v40
	v_exp_f32_e32 v40, v40
	v_add_f32_e32 v41, v82, v41
	v_mul_f32_e32 v41, 0xbfb8aa3b, v41
	v_exp_f32_e32 v41, v41
	s_nop 2
	v_add_f32_e32 v36, v83, v36
	v_mul_f32_e32 v36, 0xbfb8aa3b, v36
	v_add_f32_e32 v40, 1.0, v40
	v_exp_f32_e32 v36, v36
	v_rcp_f32_e32 v40, v40
	v_add_f32_e32 v37, v83, v37
	v_mul_f32_e32 v37, 0xbfb8aa3b, v37
	v_add_f32_e32 v36, 1.0, v36
	v_rcp_f32_e32 v109, v36
	v_mul_f32_e32 v36, v40, v86
	v_mul_f32_e32 v36, 0xbfb8aa3b, v36
	v_exp_f32_e32 v36, v36
	v_add_f32_e32 v41, 1.0, v41
	v_exp_f32_e32 v37, v37
	v_rcp_f32_e32 v41, v41
	v_fma_f32 v40, -v36, v36, 1.0
	v_max_f32_e32 v40, 0, v40
	v_add_f32_e32 v37, 1.0, v37
	v_sqrt_f32_e32 v40, v40
	s_nop 0
	v_add_f32_e32 v42, v82, v42
	v_mul_f32_e32 v42, 0xbfb8aa3b, v42
	v_exp_f32_e32 v42, v42
	v_add_f32_e32 v38, v83, v38
	v_mul_f32_e32 v38, 0xbfb8aa3b, v38
	v_add_f32_e32 v42, 1.0, v42
	v_exp_f32_e32 v38, v38
	v_rcp_f32_e32 v42, v42
	v_mul_f32_e32 v40, v109, v40
	v_rcp_f32_e32 v109, v37
	v_mul_f32_e32 v37, v41, v86
	v_mul_f32_e32 v37, 0xbfb8aa3b, v37
	v_exp_f32_e32 v37, v37
	v_add_f32_e32 v38, 1.0, v38
	ds_read_u16 v108, v106
	v_add_f32_e32 v43, v82, v43
	v_fma_f32 v41, -v37, v37, 1.0
	v_max_f32_e32 v41, 0, v41
	s_waitcnt lgkmcnt(0)
	v_lshlrev_b32_e32 v108, 16, v108
	v_sqrt_f32_e32 v41, v41
	s_nop 0
	v_mul_f32_e32 v40, v40, v108
	ds_read_u16 v108, v106 offset:272
	v_mul_f32_e32 v43, 0xbfb8aa3b, v43
	v_exp_f32_e32 v43, v43
	s_waitcnt lgkmcnt(0)
	v_lshlrev_b32_e32 v108, 16, v108
	v_add_f32_e32 v39, v83, v39
	v_mul_f32_e32 v39, 0xbfb8aa3b, v39
	v_add_f32_e32 v43, 1.0, v43
	v_mul_f32_e32 v41, v109, v41
	v_rcp_f32_e32 v109, v38
	v_mul_f32_e32 v38, v42, v86
	v_mul_f32_e32 v38, 0xbfb8aa3b, v38
	v_exp_f32_e32 v38, v38
	v_mul_f32_e32 v41, v41, v108
	ds_read_u16 v108, v106 offset:544
	v_exp_f32_e32 v39, v39
	v_fma_f32 v42, -v38, v38, 1.0
	v_max_f32_e32 v42, 0, v42
	v_rcp_f32_e32 v43, v43
	v_sqrt_f32_e32 v42, v42
	s_nop 0
	s_waitcnt lgkmcnt(0)
	v_lshlrev_b32_e32 v108, 16, v108
	v_add_f32_e32 v39, 1.0, v39
	ds_read_u16 v106, v106 offset:816
	s_waitcnt lgkmcnt(0)
	v_lshlrev_b32_e32 v106, 16, v106
	s_nop 1
	s_nop 1
	v_mul_f32_e32 v42, v109, v42
	v_mul_f32_e32 v42, v42, v108
	v_rcp_f32_e32 v108, v39
	v_mul_f32_e32 v39, v43, v86
	v_mul_f32_e32 v39, 0xbfb8aa3b, v39
	v_exp_f32_e32 v39, v39
	s_nop 0
	v_fma_f32 v43, -v39, v39, 1.0
	v_max_f32_e32 v43, 0, v43
	s_nop 0
	v_sqrt_f32_e32 v43, v43
	s_nop 0
	s_nop 0
	s_nop 0
	s_nop 1
	s_nop 1
	v_mul_f32_e32 v43, v108, v43
	v_mul_f32_e32 v43, v43, v106
	s_and_b64 vcc, exec, s[8:9]
	s_cbranch_vccnz .LBB0_167
	v_fma_f32 v108, v38, v43, v42
	v_mul_f32_e32 v109, v38, v39
	v_fma_f32 v111, v37, v108, v41
	v_mul_f32_e32 v110, v37, v109
	v_fma_f32 v112, v36, v111, v40
	v_mul_f32_e32 v106, v36, v110
	s_mov_b64 s[2:3], 0

; __device__ __forceinline__ float bf2f(bf16_t b) { return __uint_as_float(((unsigned)b) << 16); }
; __device__ __forceinline__ float sigmoidf(float z) { return __builtin_amdgcn_rcpf(1.0f + __expf(-z)); }
; __device__ void lru_fused_phase(const int bid, const int nblk, bf16_t* __restrict__ U, bf16_t* __restrict__ HF, const bf16_t* __restrict__ Wg, const float* __restrict__ cw, const float* __restrict__ cb, ...
;     ...
; #pragma unroll
;                     for (int s = 0; s < 4; ++s) {
;                         const bf16x8 af = *(const bf16x8*)(buf + (16 * rt + fr) * RS + (32 * s + 8 * fq) * 2);
;                         za = __builtin_amdgcn_mfma_f32_16x16x32_bf16(af, Bf[0][s], za, 0, 0, 0);
;                         zi = __builtin_amdgcn_mfma_f32_16x16x32_bf16(af, Bf[1][s], zi, 0, 0, 0);
;                     }
;                     float av[4], bv[4];
; #pragma unroll
;                     for (int j = 0; j < 4; ++j) {
;                         const float c = bf2f(*(const unsigned short*)(buf + (16 * rt + 4 * fq + j) * RS + chl * 2));
;                         const float r = sigmoidf(za[j] + ba), ig = sigmoidf(zi[j] + bi_);
;                         const float la = -sp * r;
;                         av[j] = __expf(la);
;                         bv[j] = __builtin_sqrtf(fmaxf(1.0f - av[j] * av[j], 0.f)) * ig * c;
;                     }
.LBB0_188:
	v_or_b32_e32 v36, s38, v47
	v_mad_u32_u24 v104, v36, s35, v104
	ds_read_b128 v[36:39], v104
	ds_read_b128 v[108:111], v104 offset:64
	s_mov_b64 s[2:3], -1
	s_waitcnt lgkmcnt(1)
	v_mfma_f32_16x16x32_bf16 v[40:43], v[36:39], v[0:3], 0
	v_mfma_f32_16x16x32_bf16 v[36:39], v[36:39], v[20:23], 0
	s_waitcnt lgkmcnt(0)
	v_mfma_f32_16x16x32_bf16 v[40:43], v[108:111], v[4:7], v[40:43]
	v_mfma_f32_16x16x32_bf16 v[36:39], v[108:111], v[24:27], v[36:39]
	ds_read_b128 v[108:111], v104 offset:128
	s_waitcnt lgkmcnt(0)
	v_mfma_f32_16x16x32_bf16 v[40:43], v[108:111], v[12:15], v[40:43]
	v_mfma_f32_16x16x32_bf16 v[36:39], v[108:111], v[28:31], v[36:39]
	ds_read_b128 v[108:111], v104 offset:192
	v_or_b32_e32 v104, s38, v46
	v_mad_u32_u24 v104, v104, s35, v10
	ds_read_u16 v10, v104
	s_waitcnt lgkmcnt(1)
	v_mfma_f32_16x16x32_bf16 v[40:43], v[108:111], v[16:19], v[40:43]
	s_waitcnt lgkmcnt(0)
	v_lshlrev_b32_e32 v105, 16, v10
	s_nop 5
	v_add_f32_e32 v10, v82, v40
	v_mul_f32_e32 v10, 0xbfb8aa3b, v10
	v_exp_f32_e32 v10, v10
	v_mfma_f32_16x16x32_bf16 v[36:39], v[108:111], v[32:35], v[36:39]
	v_add_f32_e32 v41, v82, v41
	v_mul_f32_e32 v41, 0xbfb8aa3b, v41
	v_add_f32_e32 v10, 1.0, v10
	v_rcp_f32_e32 v10, v10
	v_exp_f32_e32 v41, v41
	s_nop 2
	v_add_f32_e32 v36, v83, v36
	v_mul_f32_e32 v36, 0xbfb8aa3b, v36
	v_mul_f32_e32 v10, v10, v86
	v_mul_f32_e32 v10, 0xbfb8aa3b, v10
	v_exp_f32_e32 v10, v10
	v_exp_f32_e32 v36, v36
	v_add_f32_e32 v37, v83, v37
	v_mul_f32_e32 v37, 0xbfb8aa3b, v37
	v_fma_f32 v40, -v10, v10, 1.0
	v_max_f32_e32 v40, 0, v40
	v_add_f32_e32 v36, 1.0, v36
	v_sqrt_f32_e32 v40, v40
	s_nop 0
	v_rcp_f32_e32 v36, v36
	v_add_f32_e32 v41, 1.0, v41
	v_exp_f32_e32 v37, v37
	v_rcp_f32_e32 v41, v41
	v_add_f32_e32 v37, 1.0, v37
	v_add_f32_e32 v42, v82, v42
	v_mul_f32_e32 v42, 0xbfb8aa3b, v42
	v_exp_f32_e32 v42, v42
	v_mul_f32_e32 v36, v36, v40
	v_mul_f32_e32 v36, v36, v105
	v_rcp_f32_e32 v105, v37
	v_mul_f32_e32 v37, v41, v86
	v_mul_f32_e32 v37, 0xbfb8aa3b, v37
	v_exp_f32_e32 v37, v37
	v_add_f32_e32 v38, v83, v38
	v_mul_f32_e32 v38, 0xbfb8aa3b, v38
	v_add_f32_e32 v42, 1.0, v42
	v_fma_f32 v41, -v37, v37, 1.0
	v_max_f32_e32 v41, 0, v41
	v_exp_f32_e32 v38, v38
	v_sqrt_f32_e32 v41, v41
	s_nop 0
	v_rcp_f32_e32 v42, v42
	v_add_f32_e32 v38, 1.0, v38
	ds_read_u16 v40, v104 offset:272
	v_add_f32_e32 v43, v82, v43
	v_mul_f32_e32 v43, 0xbfb8aa3b, v43
	v_exp_f32_e32 v43, v43
	s_waitcnt lgkmcnt(0)
	v_lshlrev_b32_e32 v40, 16, v40
	v_add_f32_e32 v39, v83, v39
	v_mul_f32_e32 v41, v105, v41
	v_rcp_f32_e32 v105, v38
	v_mul_f32_e32 v38, v42, v86
	v_mul_f32_e32 v38, 0xbfb8aa3b, v38
	v_exp_f32_e32 v38, v38
	v_mul_f32_e32 v40, v41, v40
	ds_read_u16 v41, v104 offset:544
	v_mul_f32_e32 v39, 0xbfb8aa3b, v39
	v_fma_f32 v42, -v38, v38, 1.0
	v_max_f32_e32 v42, 0, v42
	v_add_f32_e32 v43, 1.0, v43
	v_sqrt_f32_e32 v42, v42
	s_nop 0
	v_exp_f32_e32 v39, v39
	v_rcp_f32_e32 v43, v43
	s_waitcnt lgkmcnt(0)
	v_lshlrev_b32_e32 v41, 16, v41
	v_add_f32_e32 v39, 1.0, v39
	s_nop 1
	s_nop 1
	v_mul_f32_e32 v42, v105, v42
	v_mul_f32_e32 v41, v42, v41
	ds_read_u16 v42, v104 offset:816
	v_rcp_f32_e32 v104, v39
	v_mul_f32_e32 v39, v43, v86
	v_mul_f32_e32 v39, 0xbfb8aa3b, v39
	v_exp_f32_e32 v39, v39
	s_waitcnt lgkmcnt(0)
	v_lshlrev_b32_e32 v42, 16, v42
	v_fma_f32 v43, -v39, v39, 1.0
	v_max_f32_e32 v43, 0, v43
	s_nop 0
	v_sqrt_f32_e32 v43, v43
	s_nop 0
	s_nop 0
	s_nop 0
	s_nop 1
	s_nop 1
	v_mul_f32_e32 v43, v104, v43
	v_mul_f32_e32 v42, v43, v42
	s_and_b64 vcc, exec, s[8:9]
	s_cbranch_vccnz .LBB0_190
	v_fma_f32 v43, v38, v42, v41
	v_mul_f32_e32 v104, v38, v39
	v_fma_f32 v108, v37, v43, v40
	v_mul_f32_e32 v107, v37, v104
	v_fma_f32 v109, v10, v108, v36
	v_mul_f32_e32 v105, v10, v107
	s_mov_b64 s[2:3], 0
